# F5 gate carry + mixer SGU: weight loads issued before the HBM tile loads
# speedup vs baseline: 1.0094x; 1.0002x over previous
.LBB0_764:
	v_lshl_add_u64 v[22:23], v[134:135], 0, s[8:9]
	global_load_dwordx4 v[138:141], v[22:23], off offset:16
	global_load_dwordx4 v[142:145], v[22:23], off
	v_lshl_add_u64 v[30:31], v[132:133], 0, s[8:9]
	global_load_dwordx4 v[146:149], v[30:31], off offset:16
	global_load_dwordx4 v[150:153], v[30:31], off
	global_load_dwordx4 v[50:53], v[22:23], off offset:144
	global_load_dwordx4 v[58:61], v[22:23], off offset:128
	global_load_dwordx4 v[54:57], v[30:31], off offset:144
	global_load_dwordx4 v[62:65], v[30:31], off offset:128
	global_load_dwordx4 v[34:37], v[22:23], off offset:272
	global_load_dwordx4 v[42:45], v[22:23], off offset:256
	global_load_dwordx4 v[38:41], v[30:31], off offset:272
	global_load_dwordx4 v[46:49], v[30:31], off offset:256
	global_load_dwordx4 v[18:21], v[22:23], off offset:400
	global_load_dwordx4 v[26:29], v[22:23], off offset:384
	s_nop 0
	global_load_dwordx4 v[22:25], v[30:31], off offset:400
	s_nop 0
	global_load_dwordx4 v[30:33], v[30:31], off offset:384
	s_waitcnt vmcnt(19)
	v_lshlrev_b32_e32 v129, 16, v2
	s_waitcnt lgkmcnt(0)
	v_sub_f32_e32 v129, v129, v136
	s_bitcmp1_b32 s11, 0
	v_mul_f32_e32 v129, v137, v129
	s_cselect_b32 s6, 0x8880, 0
	s_add_i32 s6, s6, 0
	v_lshlrev_b32_e32 v127, 1, v222
	v_and_b32_e32 v154, 0xffff0000, v2
	v_add3_u32 v127, s6, v127, v226
	v_lshlrev_b32_e32 v155, 16, v3
	v_and_b32_e32 v156, 0xffff0000, v3
	v_lshlrev_b32_e32 v157, 16, v4
	v_and_b32_e32 v158, 0xffff0000, v4
	v_lshlrev_b32_e32 v159, 16, v5
	v_and_b32_e32 v160, 0xffff0000, v5
	s_cmpk_eq_i32 s8, 0x600
	s_waitcnt vmcnt(12)
	v_fma_f32 v129, v129, v142, v150
	v_bfe_u32 v142, v129, 16, 1
	v_add3_u32 v129, v129, v142, s49
	ds_write_b16_d16_hi v127, v129 offset:1024
	v_sub_f32_e32 v129, v154, v136
	v_mul_f32_e32 v129, v137, v129
	v_fma_f32 v129, v129, v143, v151
	v_bfe_u32 v142, v129, 16, 1
	v_add3_u32 v129, v129, v142, s49
	ds_write_b16_d16_hi v127, v129 offset:1296
	v_sub_f32_e32 v129, v155, v136
	v_mul_f32_e32 v129, v137, v129
	v_fma_f32 v129, v129, v144, v152
	v_bfe_u32 v142, v129, 16, 1
	v_add3_u32 v129, v129, v142, s49
	ds_write_b16_d16_hi v127, v129 offset:1568
	v_sub_f32_e32 v129, v156, v136
	v_mul_f32_e32 v129, v137, v129
	v_fmac_f32_e32 v153, v129, v145
	v_bfe_u32 v129, v153, 16, 1
	v_add3_u32 v129, v153, v129, s49
	ds_write_b16_d16_hi v127, v129 offset:1840
	v_sub_f32_e32 v129, v157, v136
	v_mul_f32_e32 v129, v137, v129
	v_fma_f32 v129, v129, v138, v146
	v_bfe_u32 v138, v129, 16, 1
	v_add3_u32 v129, v129, v138, s49
	ds_write_b16_d16_hi v127, v129 offset:2112
	v_sub_f32_e32 v129, v158, v136
	v_mul_f32_e32 v129, v137, v129
	v_fma_f32 v129, v129, v139, v147
	v_bfe_u32 v138, v129, 16, 1
	v_add3_u32 v129, v129, v138, s49
	ds_write_b16_d16_hi v127, v129 offset:2384
	v_sub_f32_e32 v129, v159, v136
	v_mul_f32_e32 v129, v137, v129
	v_fma_f32 v129, v129, v140, v148
	v_bfe_u32 v138, v129, 16, 1
	v_add3_u32 v129, v129, v138, s49
	ds_write_b16_d16_hi v127, v129 offset:2656
	v_sub_f32_e32 v129, v160, v136
	v_mul_f32_e32 v129, v137, v129
	v_fmac_f32_e32 v149, v129, v141
	v_bfe_u32 v129, v149, 16, 1
	v_add3_u32 v129, v149, v129, s49
	ds_write_b16_d16_hi v127, v129 offset:2928
	v_lshlrev_b32_e32 v129, 16, v6
	v_sub_f32_e32 v129, v129, v136
	v_mul_f32_e32 v129, v137, v129
	s_waitcnt vmcnt(8)
	v_fma_f32 v58, v129, v58, v62
	v_bfe_u32 v62, v58, 16, 1
	v_and_b32_e32 v138, 0xffff0000, v6
	v_add3_u32 v58, v58, v62, s49
	ds_write_b16_d16_hi v127, v58 offset:9728
	v_sub_f32_e32 v58, v138, v136
	v_mul_f32_e32 v58, v137, v58
	v_fma_f32 v58, v58, v59, v63
	v_bfe_u32 v59, v58, 16, 1
	v_lshlrev_b32_e32 v139, 16, v7
	v_add3_u32 v58, v58, v59, s49
	ds_write_b16_d16_hi v127, v58 offset:10000
	v_sub_f32_e32 v58, v139, v136
	v_mul_f32_e32 v58, v137, v58
	v_fma_f32 v58, v58, v60, v64
	v_bfe_u32 v59, v58, 16, 1
	v_and_b32_e32 v140, 0xffff0000, v7
	v_add3_u32 v58, v58, v59, s49
	ds_write_b16_d16_hi v127, v58 offset:10272
	v_sub_f32_e32 v58, v140, v136
	v_mul_f32_e32 v58, v137, v58
	v_fmac_f32_e32 v65, v58, v61
	v_bfe_u32 v58, v65, 16, 1
	v_lshlrev_b32_e32 v141, 16, v8
	v_add3_u32 v58, v65, v58, s49
	ds_write_b16_d16_hi v127, v58 offset:10544
	v_sub_f32_e32 v58, v141, v136
	v_mul_f32_e32 v58, v137, v58
	v_fma_f32 v50, v58, v50, v54
	v_bfe_u32 v54, v50, 16, 1
	v_and_b32_e32 v142, 0xffff0000, v8
	v_add3_u32 v50, v50, v54, s49
	ds_write_b16_d16_hi v127, v50 offset:10816
	v_sub_f32_e32 v50, v142, v136
	v_mul_f32_e32 v50, v137, v50
	v_fma_f32 v50, v50, v51, v55
	v_bfe_u32 v51, v50, 16, 1
	v_lshlrev_b32_e32 v143, 16, v9
	v_add3_u32 v50, v50, v51, s49
	ds_write_b16_d16_hi v127, v50 offset:11088
	v_sub_f32_e32 v50, v143, v136
	v_mul_f32_e32 v50, v137, v50
	v_fma_f32 v50, v50, v52, v56
	v_bfe_u32 v51, v50, 16, 1
	v_and_b32_e32 v144, 0xffff0000, v9
	v_add3_u32 v50, v50, v51, s49
	ds_write_b16_d16_hi v127, v50 offset:11360
	v_sub_f32_e32 v50, v144, v136
	v_mul_f32_e32 v50, v137, v50
	v_fmac_f32_e32 v57, v50, v53
	v_bfe_u32 v50, v57, 16, 1
	v_add3_u32 v50, v57, v50, s49
	ds_write_b16_d16_hi v127, v50 offset:11632
	v_lshlrev_b32_e32 v50, 16, v10
	v_sub_f32_e32 v50, v50, v136
	v_mul_f32_e32 v50, v137, v50
	s_waitcnt vmcnt(4)
	v_fma_f32 v42, v50, v42, v46
	v_bfe_u32 v46, v42, 16, 1
	v_and_b32_e32 v51, 0xffff0000, v10
	v_add3_u32 v42, v42, v46, s49
	ds_write_b16_d16_hi v127, v42 offset:18432
	v_sub_f32_e32 v42, v51, v136
	v_mul_f32_e32 v42, v137, v42
	v_fma_f32 v42, v42, v43, v47
	v_bfe_u32 v43, v42, 16, 1
	v_lshlrev_b32_e32 v52, 16, v11
	v_add3_u32 v42, v42, v43, s49
	ds_write_b16_d16_hi v127, v42 offset:18704
	v_sub_f32_e32 v42, v52, v136
	v_mul_f32_e32 v42, v137, v42
	v_fma_f32 v42, v42, v44, v48
	v_bfe_u32 v43, v42, 16, 1
	v_and_b32_e32 v53, 0xffff0000, v11
	v_add3_u32 v42, v42, v43, s49
	ds_write_b16_d16_hi v127, v42 offset:18976
	v_sub_f32_e32 v42, v53, v136
	v_mul_f32_e32 v42, v137, v42
	v_fmac_f32_e32 v49, v42, v45
	v_bfe_u32 v42, v49, 16, 1
	v_lshlrev_b32_e32 v54, 16, v12
	v_add3_u32 v42, v49, v42, s49
	ds_write_b16_d16_hi v127, v42 offset:19248
	v_sub_f32_e32 v42, v54, v136
	v_mul_f32_e32 v42, v137, v42
	v_fma_f32 v34, v42, v34, v38
	v_bfe_u32 v38, v34, 16, 1
	v_and_b32_e32 v55, 0xffff0000, v12
	v_add3_u32 v34, v34, v38, s49
	ds_write_b16_d16_hi v127, v34 offset:19520
	v_sub_f32_e32 v34, v55, v136
	v_mul_f32_e32 v34, v137, v34
	v_fma_f32 v34, v34, v35, v39
	v_bfe_u32 v35, v34, 16, 1
	v_lshlrev_b32_e32 v56, 16, v13
	v_add3_u32 v34, v34, v35, s49
	ds_write_b16_d16_hi v127, v34 offset:19792
	v_sub_f32_e32 v34, v56, v136
	v_mul_f32_e32 v34, v137, v34
	v_fma_f32 v34, v34, v36, v40
	v_bfe_u32 v35, v34, 16, 1
	v_and_b32_e32 v57, 0xffff0000, v13
	v_add3_u32 v34, v34, v35, s49
	ds_write_b16_d16_hi v127, v34 offset:20064
	v_sub_f32_e32 v34, v57, v136
	v_mul_f32_e32 v34, v137, v34
	v_fmac_f32_e32 v41, v34, v37
	v_bfe_u32 v34, v41, 16, 1
	v_add3_u32 v34, v41, v34, s49
	ds_write_b16_d16_hi v127, v34 offset:20336
	v_lshlrev_b32_e32 v34, 16, v14
	v_sub_f32_e32 v34, v34, v136
	v_mul_f32_e32 v34, v137, v34
	s_waitcnt vmcnt(0)
	v_fma_f32 v26, v34, v26, v30
	v_bfe_u32 v30, v26, 16, 1
	v_and_b32_e32 v35, 0xffff0000, v14
	v_add3_u32 v26, v26, v30, s49
	ds_write_b16_d16_hi v127, v26 offset:27136
	v_sub_f32_e32 v26, v35, v136
	v_mul_f32_e32 v26, v137, v26
	v_fma_f32 v26, v26, v27, v31
	v_bfe_u32 v27, v26, 16, 1
	v_lshlrev_b32_e32 v36, 16, v15
	v_add3_u32 v26, v26, v27, s49
	ds_write_b16_d16_hi v127, v26 offset:27408
	v_sub_f32_e32 v26, v36, v136
	v_mul_f32_e32 v26, v137, v26
	v_fma_f32 v26, v26, v28, v32
	v_bfe_u32 v27, v26, 16, 1
	v_and_b32_e32 v37, 0xffff0000, v15
	v_add3_u32 v26, v26, v27, s49
	ds_write_b16_d16_hi v127, v26 offset:27680
	v_sub_f32_e32 v26, v37, v136
	v_mul_f32_e32 v26, v137, v26
	v_fmac_f32_e32 v33, v26, v29
	v_bfe_u32 v26, v33, 16, 1
	v_lshlrev_b32_e32 v38, 16, v16
	v_add3_u32 v26, v33, v26, s49
	ds_write_b16_d16_hi v127, v26 offset:27952
	v_sub_f32_e32 v26, v38, v136
	v_mul_f32_e32 v26, v137, v26
	v_fma_f32 v18, v26, v18, v22
	v_bfe_u32 v22, v18, 16, 1
	v_and_b32_e32 v39, 0xffff0000, v16
	v_add3_u32 v18, v18, v22, s49
	ds_write_b16_d16_hi v127, v18 offset:28224
	v_sub_f32_e32 v18, v39, v136
	v_mul_f32_e32 v18, v137, v18
	v_fma_f32 v18, v18, v19, v23
	v_bfe_u32 v19, v18, 16, 1
	v_lshlrev_b32_e32 v40, 16, v17
	v_add3_u32 v18, v18, v19, s49
	ds_write_b16_d16_hi v127, v18 offset:28496
	v_sub_f32_e32 v18, v40, v136
	v_mul_f32_e32 v18, v137, v18
	v_fma_f32 v18, v18, v20, v24
	v_bfe_u32 v19, v18, 16, 1
	v_and_b32_e32 v41, 0xffff0000, v17
	v_add3_u32 v18, v18, v19, s49
	ds_write_b16_d16_hi v127, v18 offset:28768
	v_sub_f32_e32 v18, v41, v136
	v_mul_f32_e32 v18, v137, v18
	v_fmac_f32_e32 v25, v18, v21
	v_bfe_u32 v18, v25, 16, 1
	v_add3_u32 v18, v25, v18, s49
	ds_write_b16_d16_hi v127, v18 offset:29040
	v_lshl_add_u64 v[250:251], s[56:57], 0, v[72:73]
	v_add_co_u32_e32 v250, vcc, 0xcd00000, v250
	s_nop 1
	v_addc_co_u32_e32 v251, vcc, 0, v251, vcc
	global_load_dwordx4 v[26:29], v[250:251], off
	global_load_dwordx4 v[18:21], v[250:251], off offset:64
	global_load_dwordx4 v[42:45], v[250:251], off offset:128
	global_load_dwordx4 v[22:25], v[250:251], off offset:192
	v_lshl_add_u64 v[252:253], v[68:69], 0, s[8:9]
	global_load_dword v58, v[252:253], off
	v_lshl_add_u64 v[252:253], s[56:57], 0, v[130:131]
	v_add_co_u32_e32 v252, vcc, 0x32000000, v252
	v_add_u32_e32 v30, s6, v84
	s_nop 0
	v_addc_co_u32_e32 v253, vcc, 0, v253, vcc
	global_load_dwordx2 v[146:147], v[252:253], off nt
	global_load_dwordx2 v[144:145], v[252:253], off offset:32 nt
	global_load_dwordx2 v[142:143], v[252:253], off offset:64 nt
	global_load_dwordx2 v[140:141], v[252:253], off offset:96 nt
	global_load_dwordx2 v[138:139], v[252:253], off offset:128 nt
	global_load_dwordx2 v[64:65], v[252:253], off offset:160 nt
	global_load_dwordx2 v[62:63], v[252:253], off offset:192 nt
	global_load_dwordx2 v[60:61], v[252:253], off offset:224 nt
	v_add_u32_e32 v59, v30, v227
	s_cbranch_scc1 .LBB0_766
	v_lshl_add_u64 v[2:3], s[56:57], 0, v[70:71]
	v_add_co_u32_e32 v14, vcc, 0x32000000, v2
	s_nop 1
	v_addc_co_u32_e32 v15, vcc, 0, v3, vcc
	global_load_dwordx4 v[2:5], v[14:15], off offset:2304 nt
	global_load_dwordx4 v[6:9], v[14:15], off offset:2368 nt
	global_load_dwordx4 v[10:13], v[14:15], off offset:2432 nt
	s_nop 0
	global_load_dwordx4 v[14:17], v[14:15], off offset:2496 nt
.LBB0_766:
	s_waitcnt lgkmcnt(0)
	s_waitcnt lgkmcnt(0)
	s_barrier
	ds_read_b128 v[38:41], v59 offset:9728
	ds_read_b128 v[46:49], v59 offset:14080
	ds_read_b128 v[30:33], v59 offset:1024
	ds_read_b128 v[34:37], v59 offset:5376
	v_cndmask_b32_e64 v127, 0, 1, s[62:63]
	v_cmp_ne_u32_e64 s[6:7], 1, v127
	s_andn2_b64 vcc, exec, s[62:63]
	s_waitcnt vmcnt(12) lgkmcnt(2)
	v_mfma_f32_16x16x32_bf16 v[148:151], v[46:49], v[26:29], 0
	ds_read_b128 v[46:49], v59 offset:18432
	s_waitcnt lgkmcnt(0)
	v_mfma_f32_16x16x32_bf16 v[152:155], v[46:49], v[26:29], 0
	ds_read_b128 v[46:49], v59 offset:22784
	s_waitcnt lgkmcnt(0)
	v_mfma_f32_16x16x32_bf16 v[156:159], v[46:49], v[26:29], 0
	ds_read_b128 v[46:49], v59 offset:27136
	s_waitcnt lgkmcnt(0)
	v_mfma_f32_16x16x32_bf16 v[172:175], v[46:49], v[26:29], 0
	ds_read_b128 v[46:49], v59 offset:31488
	v_mfma_f32_16x16x32_bf16 v[30:33], v[30:33], v[26:29], 0
	v_mfma_f32_16x16x32_bf16 v[34:37], v[34:37], v[26:29], 0
	v_mfma_f32_16x16x32_bf16 v[38:41], v[38:41], v[26:29], 0
	s_waitcnt lgkmcnt(0)
	v_mfma_f32_16x16x32_bf16 v[176:179], v[46:49], v[26:29], 0
	ds_read_b128 v[26:29], v59 offset:1088
	s_waitcnt vmcnt(11) lgkmcnt(0)
	v_mfma_f32_16x16x32_bf16 v[54:57], v[26:29], v[18:21], v[30:33]
	ds_read_b128 v[26:29], v59 offset:5440
	s_waitcnt lgkmcnt(0)
	v_mfma_f32_16x16x32_bf16 v[50:53], v[26:29], v[18:21], v[34:37]
	ds_read_b128 v[26:29], v59 offset:9792
	s_waitcnt lgkmcnt(0)
	v_mfma_f32_16x16x32_bf16 v[46:49], v[26:29], v[18:21], v[38:41]
	ds_read_b128 v[26:29], v59 offset:14144
	s_waitcnt lgkmcnt(0)
	v_mfma_f32_16x16x32_bf16 v[38:41], v[26:29], v[18:21], v[148:151]
	ds_read_b128 v[26:29], v59 offset:18496
	s_nop 1
	ds_read_b128 v[148:151], v59 offset:31552
	s_waitcnt lgkmcnt(1)
	v_mfma_f32_16x16x32_bf16 v[34:37], v[26:29], v[18:21], v[152:155]
	ds_read_b128 v[26:29], v59 offset:22848
	s_waitcnt lgkmcnt(0)
	v_mfma_f32_16x16x32_bf16 v[30:33], v[26:29], v[18:21], v[156:159]
	ds_read_b128 v[26:29], v59 offset:27200
	s_waitcnt lgkmcnt(0)
	v_mfma_f32_16x16x32_bf16 v[26:29], v[26:29], v[18:21], v[172:175]
	v_mfma_f32_16x16x32_bf16 v[18:21], v[148:151], v[18:21], v[176:179]
	s_cbranch_vccnz .LBB0_768
	ds_read_b128 v[148:151], v59 offset:1152
	s_waitcnt vmcnt(10) lgkmcnt(0)
	v_mfma_f32_16x16x32_bf16 v[54:57], v[148:151], v[42:45], v[54:57]
	ds_read_b128 v[148:151], v59 offset:5504
	s_waitcnt lgkmcnt(0)
	v_mfma_f32_16x16x32_bf16 v[50:53], v[148:151], v[42:45], v[50:53]
	ds_read_b128 v[148:151], v59 offset:9856
	s_waitcnt lgkmcnt(0)
	v_mfma_f32_16x16x32_bf16 v[46:49], v[148:151], v[42:45], v[46:49]
	ds_read_b128 v[148:151], v59 offset:14208
	s_waitcnt lgkmcnt(0)
	v_mfma_f32_16x16x32_bf16 v[38:41], v[148:151], v[42:45], v[38:41]
	ds_read_b128 v[148:151], v59 offset:18560
	s_waitcnt lgkmcnt(0)
	v_mfma_f32_16x16x32_bf16 v[34:37], v[148:151], v[42:45], v[34:37]
	ds_read_b128 v[148:151], v59 offset:22912
	s_waitcnt lgkmcnt(0)
	v_mfma_f32_16x16x32_bf16 v[30:33], v[148:151], v[42:45], v[30:33]
	ds_read_b128 v[148:151], v59 offset:27264
	s_waitcnt lgkmcnt(0)
	v_mfma_f32_16x16x32_bf16 v[26:29], v[148:151], v[42:45], v[26:29]
	ds_read_b128 v[148:151], v59 offset:31616
	s_waitcnt lgkmcnt(0)
	v_mfma_f32_16x16x32_bf16 v[18:21], v[148:151], v[42:45], v[18:21]
.LBB0_768:
	s_and_b64 vcc, exec, s[6:7]
	s_cbranch_vccnz .LBB0_763
	s_waitcnt vmcnt(10)
	ds_read_b128 v[42:45], v59 offset:1216
	s_waitcnt vmcnt(9) lgkmcnt(0)
	v_mfma_f32_16x16x32_bf16 v[54:57], v[42:45], v[22:25], v[54:57]
	ds_read_b128 v[42:45], v59 offset:5568
	s_waitcnt lgkmcnt(0)
	v_mfma_f32_16x16x32_bf16 v[50:53], v[42:45], v[22:25], v[50:53]
	ds_read_b128 v[42:45], v59 offset:9920
	s_waitcnt lgkmcnt(0)
	v_mfma_f32_16x16x32_bf16 v[46:49], v[42:45], v[22:25], v[46:49]
	ds_read_b128 v[42:45], v59 offset:14272
	s_waitcnt lgkmcnt(0)
	v_mfma_f32_16x16x32_bf16 v[38:41], v[42:45], v[22:25], v[38:41]
	ds_read_b128 v[42:45], v59 offset:18624
	s_waitcnt lgkmcnt(0)
	v_mfma_f32_16x16x32_bf16 v[34:37], v[42:45], v[22:25], v[34:37]
	ds_read_b128 v[42:45], v59 offset:22976
	s_waitcnt lgkmcnt(0)
	v_mfma_f32_16x16x32_bf16 v[30:33], v[42:45], v[22:25], v[30:33]
	ds_read_b128 v[42:45], v59 offset:27328
	s_waitcnt lgkmcnt(0)
	v_mfma_f32_16x16x32_bf16 v[26:29], v[42:45], v[22:25], v[26:29]
	ds_read_b128 v[42:45], v59 offset:31680
	s_waitcnt lgkmcnt(0)
	v_mfma_f32_16x16x32_bf16 v[18:21], v[42:45], v[22:25], v[18:21]
	s_branch .LBB0_763
